# Attention q-block assignment rebalanced: round k takes c0, 63-c0, (c0+32)&63, 63-((c0+32)&63) so every wave gets 55..58 key tiles instead of 49..64
# speedup vs baseline: 1.0086x; 1.0086x over previous
.LBB0_128:
	s_lshr_b32 s4, s19, 1
	s_lshl_b32 s4, s4, 5
	s_add_i32 s4, s4, s97
	s_and_b32 s4, s4, 63
	s_and_b32 s5, s19, 1
	s_sub_i32 s5, 0, s5
	s_and_b32 s5, s5, 63
	s_xor_b32 s4, s4, s5
	s_ashr_i32 s5, s4, 31
	s_lshr_b32 s5, s5, 26
	s_add_i32 s5, s4, s5
	s_andn2_b32 s5, s5, 63
	s_sub_i32 s4, s4, s5
	s_lshl_b32 s5, s4, 5
	s_and_b32 s26, s5, 0xffffff80
	s_and_b32 s27, s4, 3
	s_or_b32 s58, s26, s27
	s_cmpk_gt_i32 s58, 0x60
	s_mov_b32 s74, 0
	s_cbranch_scc1 .LBB0_133
	s_cmp_gt_i32 s58, 64
	s_mov_b32 s74, 1
	s_cbranch_scc1 .LBB0_133
	s_cmp_gt_i32 s58, 32
	s_mov_b32 s74, 2
	s_cbranch_scc1 .LBB0_133
	s_cmp_gt_i32 s58, 0
	s_mov_b32 s74, 3
	s_cbranch_scc1 .LBB0_133
	s_cmp_gt_u32 s58, 0xffffff80
	s_cselect_b32 s4, 7, 23
	s_cmpk_lt_i32 s58, 0xffe1
	s_cselect_b32 s74, s4, 4
.LBB0_133:
	s_lshl_b32 s4, s19, 2
	s_add_i32 s4, s4, s17
	s_add_i32 s18, s19, 1
	s_cmp_lg_u32 s19, 3
	s_cselect_b32 s5, s18, 3
	s_lshl_b32 s6, s5, 2
	s_lshr_b32 s7, s5, 1
	s_lshl_b32 s7, s7, 5
	s_add_i32 s7, s7, s97
	s_and_b32 s7, s7, 63
	s_and_b32 s5, s5, 1
	s_sub_i32 s5, 0, s5
	s_and_b32 s5, s5, 63
	s_xor_b32 s5, s7, s5
	s_ashr_i32 s7, s5, 31
	s_add_i32 s6, s6, s17
	s_lshr_b32 s7, s7, 26
	s_add_i32 s7, s5, s7
	s_ashr_i32 s28, s4, 3
	s_and_b32 s19, s4, 7
	s_ashr_i32 s4, s6, 3
	s_andn2_b32 s7, s7, 63
	s_mul_hi_i32 s35, s4, 0xc00000
	s_mul_i32 s34, s4, 0xc00000
	s_add_i32 s4, s19, 1
	s_sub_i32 s5, s5, s7
	v_cvt_f32_ubyte0_e32 v0, s4
	s_and_b32 s65, s6, 7
	s_lshl_b32 s6, s5, 5
	v_exp_f32_e64 v0, -v0
	s_and_b32 s6, s6, 0xffffff80
	s_and_b32 s5, s5, 3
	s_or_b32 s66, s6, s5
	s_ashr_i32 s29, s28, 31
	s_add_i32 s67, s58, 0x300
	s_add_i32 s68, s58, 0xfffffa00
	s_waitcnt vmcnt(25)
	v_or_b32_e32 v144, s58, v148
	s_cmp_gt_u32 s66, 0xffffff80
	v_mul_f32_e32 v141, 0xbfb8aa3b, v0
	v_min_i32_e32 v0, 0x200, v144
	s_cselect_b32 s4, 7, 23
	s_cmpk_lt_i32 s66, 0xffe1
	v_cvt_f32_i32_e32 v0, v0
	v_cvt_f32_i32_e32 v2, v144
	s_cselect_b32 s4, s4, 4
	s_cmp_lt_i32 s66, 1
	s_cselect_b32 s4, s4, 3
	s_cmp_lt_i32 s66, 33
	s_cselect_b32 s4, s4, 2
	s_cmpk_lt_i32 s66, 0x41
	s_cselect_b32 s4, s4, 1
	s_cmpk_lt_i32 s66, 0x61
	v_mov_b32_e32 v14, v1
	v_mov_b32_e32 v15, v1
	v_mul_f32_e32 v145, 0.5, v0
	v_mul_f32_e32 v161, 0.5, v2
	s_cselect_b32 s69, s4, 0
	s_add_i32 s70, s26, s27
	v_mov_b32_e32 v0, v1
	v_mov_b32_e32 v2, v1
	s_waitcnt vmcnt(4)
	v_mov_b32_e32 v3, v1
	v_mov_b32_e32 v4, v1
	v_mov_b32_e32 v5, v1
	v_mov_b32_e32 v6, v1
	v_mov_b32_e32 v7, v1
	v_mov_b32_e32 v8, v1
	v_mov_b32_e32 v9, v1
	v_mov_b32_e32 v10, v1
	v_mov_b32_e32 v11, v1
	v_mov_b32_e32 v12, v1
	v_mov_b32_e32 v13, v1
	s_waitcnt vmcnt(12)
	v_mov_b64_e32 v[30:31], v[14:15]
	v_mov_b64_e32 v[46:47], v[14:15]
	s_mul_hi_i32 s31, s28, 0xc00000
	s_mul_i32 s30, s28, 0xc00000
	s_addk_i32 s70, 0xffa0
	v_mov_b32_e32 v143, 0
	v_mov_b32_e32 v162, 0xf149f2ca
	v_mov_b64_e32 v[28:29], v[12:13]
	v_mov_b64_e32 v[26:27], v[10:11]
	v_mov_b64_e32 v[24:25], v[8:9]
	v_mov_b64_e32 v[22:23], v[6:7]
	v_mov_b64_e32 v[20:21], v[4:5]
	v_mov_b64_e32 v[18:19], v[2:3]
	v_mov_b64_e32 v[16:17], v[0:1]
	v_mov_b64_e32 v[44:45], v[12:13]
	v_mov_b64_e32 v[42:43], v[10:11]
	v_mov_b64_e32 v[40:41], v[8:9]
	v_mov_b64_e32 v[38:39], v[6:7]
	v_mov_b64_e32 v[36:37], v[4:5]
	v_mov_b64_e32 v[34:35], v[2:3]
	v_mov_b64_e32 v[32:33], v[0:1]
	s_branch .LBB0_135
